# MLA: MFMA<->VALU interleave - first score block's exps issued in the shadow of the second block's QK^T MFMAs (fast path for non-diagonal fixed-shift tiles)
# baseline (speedup 1.0000x reference)
; #define MFMA32(a, b, c) __builtin_amdgcn_mfma_f32_32x32x16_bf16((a), (b), (c), 0, 0, 0)
; #define AT_SB __builtin_amdgcn_sched_barrier(0);
; template <int DQK, int MODE, bool QN, bool KN> ...
;     ...
;     if (active) {
;       f32x16 sacc[2];
;       const float sinit = fixed_shift ? -sbound : 0.f;
; #pragma unroll
;       for (int kb = 0; kb < 2; ++kb) {
; #pragma unroll
;         for (int i = 0; i < 16; ++i) sacc[kb][i] = sinit;
; #pragma unroll
;         for (int s = 0; s < NS; ++s) {
;           const bf16x8 kf = *(const bf16x8*)(sK + (kb * 32 + r) * KROW + s * 32 + h * 16);
;           sacc[kb] = MFMA32(kf, qf[s], sacc[kb]);
;         }
;       }
;       const bool diag = (MODE != 0) && (kt * 64 + 63 >= q0 + wave * 32);
;       if (MODE != 0 && diag) {
; #pragma unroll
;         for (int kb = 0; kb < 2; ++kb)
; #pragma unroll
;           for (int i = 0; i < 16; ++i) {
;             const int key = kt * 64 + kb * 32 + (i & 3) + 8 * (i >> 2) + 4 * h;
;             if (MODE == 1 ? (key > qrow) : (key >= qrow)) sacc[kb][i] = -INFINITY;
;           }
;       }
;     ...
;     AT_SB AT_GLOAD(rk0, rv0, sg + 2)
;     AT_SB compute(2 * sg, 0); compute(2 * sg + 1, 0); AT_SB
.Lstg_a:
	s_add_i32 s55, s45, -1
	s_min_i32 s2, s55, s13
	s_lshl_b32 s4, s2, 7
	v_add_u32_e32 v0, s4, v238
	v_mad_i64_i32 v[2:3], s[2:3], v0, s36, v[220:221]
	v_add_u32_e32 v0, s4, v239
	v_mad_i64_i32 v[6:7], s[2:3], v0, s36, v[222:223]
	v_add_u32_e32 v0, s4, v240
	v_mad_i64_i32 v[10:11], s[2:3], v0, s36, v[224:225]
	v_add_u32_e32 v0, s4, v241
	v_mad_i64_i32 v[14:15], s[2:3], v0, s37, v[218:219]
	v_add_u32_e32 v0, s4, v242
	global_load_dwordx4 v[2:5], v[2:3], off
	s_nop 0
	global_load_dwordx4 v[6:9], v[6:7], off
	s_nop 0
	global_load_dwordx4 v[10:13], v[10:11], off
	s_nop 0
	global_load_dwordx4 v[204:207], v[14:15], off
	v_mad_i64_i32 v[14:15], s[2:3], v0, s37, v[218:219]
	global_load_dwordx4 v[208:211], v[14:15], off
	s_add_i32 s2, s53, 0xffffff01
	v_cmp_le_i32_e32 vcc, s2, v243
	s_and_saveexec_b64 s[2:3], vcc
	s_cbranch_execz .LBB0_1208
	ds_read_b128 v[32:35], v251
	ds_read_b128 v[36:39], v251 offset:32
	ds_read_b128 v[40:43], v251 offset:64
	ds_read_b128 v[44:47], v251 offset:96
	ds_read_b128 v[48:51], v251 offset:128
	ds_read_b128 v[52:55], v251 offset:160
	ds_read_b128 v[112:115], v251 offset:6656
	ds_read_b128 v[116:119], v251 offset:6688
	ds_read_b128 v[120:123], v251 offset:6720
	ds_read_b128 v[124:127], v251 offset:6752
	ds_read_b128 v[144:147], v251 offset:6784
	ds_read_b128 v[148:151], v251 offset:6816
	s_add_i32 s4, s53, 0xffffff40
	v_cmp_ge_i32_e32 vcc, s4, v236
	s_waitcnt lgkmcnt(11)
	v_mfma_f32_32x32x16_bf16 v[80:95], v[32:35], v[160:163], v[16:31]
	s_waitcnt lgkmcnt(10)
	v_mfma_f32_32x32x16_bf16 v[80:95], v[36:39], v[164:167], v[80:95]
	s_waitcnt lgkmcnt(9)
	v_mfma_f32_32x32x16_bf16 v[80:95], v[40:43], v[168:171], v[80:95]
	s_waitcnt lgkmcnt(8)
	v_mfma_f32_32x32x16_bf16 v[80:95], v[44:47], v[172:175], v[80:95]
	s_waitcnt lgkmcnt(7)
	v_mfma_f32_32x32x16_bf16 v[80:95], v[48:51], v[176:179], v[80:95]
	s_waitcnt lgkmcnt(6)
	v_mfma_f32_32x32x16_bf16 v[80:95], v[52:55], v[180:183], v[80:95]
	s_or_b64 s[10:11], s[0:1], vcc
	s_cbranch_scc0 .Lmfp_0
	s_waitcnt lgkmcnt(5)
	v_mfma_f32_32x32x16_bf16 v[64:79], v[112:115], v[160:163], v[16:31]
	s_waitcnt lgkmcnt(4)
	v_mfma_f32_32x32x16_bf16 v[64:79], v[116:119], v[164:167], v[64:79]
	s_waitcnt lgkmcnt(3)
	v_mfma_f32_32x32x16_bf16 v[64:79], v[120:123], v[168:171], v[64:79]
	s_waitcnt lgkmcnt(2)
	v_mfma_f32_32x32x16_bf16 v[64:79], v[124:127], v[172:175], v[64:79]
	s_waitcnt lgkmcnt(1)
	v_mfma_f32_32x32x16_bf16 v[64:79], v[144:147], v[176:179], v[64:79]
	s_waitcnt lgkmcnt(0)
	v_mfma_f32_32x32x16_bf16 v[64:79], v[148:151], v[180:183], v[64:79]
	s_and_saveexec_b64 s[10:11], vcc
	s_cbranch_execz .LBB0_1201
	v_add_u32_e32 v0, s53, v247
	v_add_u32_e32 v14, 0xffffff01, v0
	v_cmp_lt_i32_e32 vcc, v14, v237
	s_nop 1
	v_cndmask_b32_e32 v81, v234, v81, vcc
	v_cmp_le_i32_e32 vcc, v14, v237
	v_add_u32_e32 v14, 0xffffff03, v0
	s_nop 0
	v_cndmask_b32_e32 v80, v234, v80, vcc
	v_cmp_le_i32_e32 vcc, v14, v237
	v_add_u32_e32 v14, 0xffffff04, v0
	s_nop 0
	v_cndmask_b32_e32 v82, v234, v82, vcc
	v_cmp_le_i32_e32 vcc, v14, v237
	v_add_u32_e32 v14, 0xffffff09, v0
	s_nop 0
	v_cndmask_b32_e32 v83, v234, v83, vcc
	v_cmp_le_i32_e32 vcc, v14, v237
	v_add_u32_e32 v14, 0xffffff0a, v0
	s_nop 0
	v_cndmask_b32_e32 v84, v234, v84, vcc
	v_cmp_le_i32_e32 vcc, v14, v237
	v_add_u32_e32 v14, 0xffffff0b, v0
	s_nop 0
	v_cndmask_b32_e32 v85, v234, v85, vcc
	v_cmp_le_i32_e32 vcc, v14, v237
	v_add_u32_e32 v14, 0xffffff0c, v0
	s_nop 0
	v_cndmask_b32_e32 v86, v234, v86, vcc
	v_cmp_le_i32_e32 vcc, v14, v237
	v_add_u32_e32 v14, 0xffffff11, v0
	s_nop 0
	v_cndmask_b32_e32 v87, v234, v87, vcc
	v_cmp_le_i32_e32 vcc, v14, v237
	v_add_u32_e32 v14, 0xffffff12, v0
	s_nop 0
	v_cndmask_b32_e32 v88, v234, v88, vcc
	v_cmp_le_i32_e32 vcc, v14, v237
	v_add_u32_e32 v14, 0xffffff13, v0
	s_nop 0
	v_cndmask_b32_e32 v89, v234, v89, vcc
	v_cmp_le_i32_e32 vcc, v14, v237
	v_add_u32_e32 v14, 0xffffff14, v0
	s_nop 0
	v_cndmask_b32_e32 v90, v234, v90, vcc
	v_cmp_le_i32_e32 vcc, v14, v237
	v_add_u32_e32 v14, 0xffffff19, v0
	s_nop 0
	v_cndmask_b32_e32 v91, v234, v91, vcc
	v_cmp_le_i32_e32 vcc, v14, v237
	v_add_u32_e32 v14, 0xffffff1a, v0
	s_nop 0
	v_cndmask_b32_e32 v92, v234, v92, vcc
	v_cmp_le_i32_e32 vcc, v14, v237
	v_add_u32_e32 v14, 0xffffff1b, v0
	s_nop 0
	v_cndmask_b32_e32 v93, v234, v93, vcc
	v_cmp_le_i32_e32 vcc, v14, v237
	v_add_u32_e32 v14, 0xffffff1c, v0
	s_nop 0
	v_cndmask_b32_e32 v94, v234, v94, vcc
	v_cmp_le_i32_e32 vcc, v14, v237
	v_add_u32_e32 v14, 0xffffff21, v0
	s_nop 0
	v_cndmask_b32_e32 v95, v234, v95, vcc
	v_cmp_le_i32_e32 vcc, v14, v237
	v_add_u32_e32 v14, 0xffffff22, v0
	s_nop 0
	v_cndmask_b32_e32 v64, v234, v64, vcc
	v_cmp_le_i32_e32 vcc, v14, v237
	v_add_u32_e32 v14, 0xffffff23, v0
	s_nop 0
	v_cndmask_b32_e32 v65, v234, v65, vcc
	v_cmp_le_i32_e32 vcc, v14, v237
	v_add_u32_e32 v14, 0xffffff24, v0
	s_nop 0
	v_cndmask_b32_e32 v66, v234, v66, vcc
	v_cmp_le_i32_e32 vcc, v14, v237
	v_add_u32_e32 v14, 0xffffff29, v0
	s_nop 0
	v_cndmask_b32_e32 v67, v234, v67, vcc
	v_cmp_le_i32_e32 vcc, v14, v237
	v_add_u32_e32 v14, 0xffffff2a, v0
	s_nop 0
	v_cndmask_b32_e32 v68, v234, v68, vcc
	v_cmp_le_i32_e32 vcc, v14, v237
	v_add_u32_e32 v14, 0xffffff2b, v0
	s_nop 0
	v_cndmask_b32_e32 v69, v234, v69, vcc
	v_cmp_le_i32_e32 vcc, v14, v237
	v_add_u32_e32 v14, 0xffffff2c, v0
	s_nop 0
	v_cndmask_b32_e32 v70, v234, v70, vcc
	v_cmp_le_i32_e32 vcc, v14, v237
	v_add_u32_e32 v14, 0xffffff31, v0
	s_nop 0
	v_cndmask_b32_e32 v71, v234, v71, vcc
	v_cmp_le_i32_e32 vcc, v14, v237
	v_add_u32_e32 v14, 0xffffff32, v0
	s_nop 0
	v_cndmask_b32_e32 v72, v234, v72, vcc
	v_cmp_le_i32_e32 vcc, v14, v237
	v_add_u32_e32 v14, 0xffffff33, v0
	s_nop 0
	v_cndmask_b32_e32 v73, v234, v73, vcc
	v_cmp_le_i32_e32 vcc, v14, v237
	v_add_u32_e32 v14, 0xffffff34, v0
	s_nop 0
	v_cndmask_b32_e32 v74, v234, v74, vcc
	v_cmp_le_i32_e32 vcc, v14, v237
	v_add_u32_e32 v14, 0xffffff39, v0
	s_nop 0
	v_cndmask_b32_e32 v75, v234, v75, vcc
	v_cmp_le_i32_e32 vcc, v14, v237
	v_add_u32_e32 v14, 0xffffff3a, v0
	s_nop 0
	v_cndmask_b32_e32 v76, v234, v76, vcc
	v_cmp_le_i32_e32 vcc, v14, v237
	v_add_u32_e32 v14, 0xffffff3b, v0
	v_add_u32_e32 v0, 0xffffff3c, v0
	v_cndmask_b32_e32 v77, v234, v77, vcc
	v_cmp_le_i32_e32 vcc, v14, v237
	s_nop 1
	v_cndmask_b32_e32 v78, v234, v78, vcc
	v_cmp_le_i32_e32 vcc, v0, v237
	s_nop 1
	v_cndmask_b32_e32 v79, v234, v79, vcc

; #define MFMA32(a, b, c) __builtin_amdgcn_mfma_f32_32x32x16_bf16((a), (b), (c), 0, 0, 0)
; template <int DQK, int MODE, bool QN, bool KN> ...
;     ...
;     if (active) {
;       f32x16 sacc[2];
;       const float sinit = fixed_shift ? -sbound : 0.f;
; #pragma unroll
;       for (int kb = 0; kb < 2; ++kb) {
; #pragma unroll
;         for (int i = 0; i < 16; ++i) sacc[kb][i] = sinit;
; #pragma unroll
;         for (int s = 0; s < NS; ++s) {
;           const bf16x8 kf = *(const bf16x8*)(sK + (kb * 32 + r) * KROW + s * 32 + h * 16);
;           sacc[kb] = MFMA32(kf, qf[s], sacc[kb]);
;         }
;       }
;       const bool diag = (MODE != 0) && (kt * 64 + 63 >= q0 + wave * 32);
;       if (MODE != 0 && diag) {
; #pragma unroll
;         for (int kb = 0; kb < 2; ++kb)
; #pragma unroll
;           for (int i = 0; i < 16; ++i) {
;             const int key = kt * 64 + kb * 32 + (i & 3) + 8 * (i >> 2) + 4 * h;
;             if (MODE == 1 ? (key > qrow) : (key >= qrow)) sacc[kb][i] = -INFINITY;
;           }
;       }
.LBB0_1208:
	s_or_b64 exec, exec, s[2:3]
	s_add_i32 s2, s53, 0xffffff41
	v_cmp_le_i32_e32 vcc, s2, v243
	s_and_saveexec_b64 s[2:3], vcc
	s_cbranch_execz .LBB0_1218
	ds_read_b128 v[32:35], v251 offset:13312
	ds_read_b128 v[36:39], v251 offset:13344
	ds_read_b128 v[40:43], v251 offset:13376
	ds_read_b128 v[44:47], v251 offset:13408
	ds_read_b128 v[48:51], v251 offset:13440
	ds_read_b128 v[52:55], v251 offset:13472
	ds_read_b128 v[112:115], v251 offset:19968
	ds_read_b128 v[116:119], v251 offset:20000
	ds_read_b128 v[120:123], v251 offset:20032
	ds_read_b128 v[124:127], v251 offset:20064
	ds_read_b128 v[144:147], v251 offset:20096
	ds_read_b128 v[148:151], v251 offset:20128
	s_add_i32 s4, s53, 0xffffff80
	v_cmp_ge_i32_e32 vcc, s4, v236
	s_waitcnt lgkmcnt(11)
	v_mfma_f32_32x32x16_bf16 v[80:95], v[32:35], v[160:163], v[16:31]
	s_waitcnt lgkmcnt(10)
	v_mfma_f32_32x32x16_bf16 v[80:95], v[36:39], v[164:167], v[80:95]
	s_waitcnt lgkmcnt(9)
	v_mfma_f32_32x32x16_bf16 v[80:95], v[40:43], v[168:171], v[80:95]
	s_waitcnt lgkmcnt(8)
	v_mfma_f32_32x32x16_bf16 v[80:95], v[44:47], v[172:175], v[80:95]
	s_waitcnt lgkmcnt(7)
	v_mfma_f32_32x32x16_bf16 v[80:95], v[48:51], v[176:179], v[80:95]
	s_waitcnt lgkmcnt(6)
	v_mfma_f32_32x32x16_bf16 v[80:95], v[52:55], v[180:183], v[80:95]
	s_or_b64 s[10:11], s[0:1], vcc
	s_cbranch_scc0 .Lmfp_1
	s_waitcnt lgkmcnt(5)
	v_mfma_f32_32x32x16_bf16 v[64:79], v[112:115], v[160:163], v[16:31]
	s_waitcnt lgkmcnt(4)
	v_mfma_f32_32x32x16_bf16 v[64:79], v[116:119], v[164:167], v[64:79]
	s_waitcnt lgkmcnt(3)
	v_mfma_f32_32x32x16_bf16 v[64:79], v[120:123], v[168:171], v[64:79]
	s_waitcnt lgkmcnt(2)
	v_mfma_f32_32x32x16_bf16 v[64:79], v[124:127], v[172:175], v[64:79]
	s_waitcnt lgkmcnt(1)
	v_mfma_f32_32x32x16_bf16 v[64:79], v[144:147], v[176:179], v[64:79]
	s_waitcnt lgkmcnt(0)
	v_mfma_f32_32x32x16_bf16 v[64:79], v[148:151], v[180:183], v[64:79]
	s_and_saveexec_b64 s[10:11], vcc
	s_cbranch_execz .LBB0_1211
	v_add_u32_e32 v0, s53, v247
	v_add_u32_e32 v14, 0xffffff41, v0
	v_cmp_le_i32_e32 vcc, v14, v237
	v_add_u32_e32 v14, 0xffffff42, v0
	s_nop 0
	v_cndmask_b32_e32 v80, v234, v80, vcc
	v_cmp_le_i32_e32 vcc, v14, v237
	v_add_u32_e32 v14, 0xffffff43, v0
	s_nop 0
	v_cndmask_b32_e32 v81, v234, v81, vcc
	v_cmp_le_i32_e32 vcc, v14, v237
	v_add_u32_e32 v14, 0xffffff44, v0
	s_nop 0
	v_cndmask_b32_e32 v82, v234, v82, vcc
	v_cmp_le_i32_e32 vcc, v14, v237
	v_add_u32_e32 v14, 0xffffff49, v0
	s_nop 0
	v_cndmask_b32_e32 v83, v234, v83, vcc
	v_cmp_le_i32_e32 vcc, v14, v237
	v_add_u32_e32 v14, 0xffffff4a, v0
	s_nop 0
	v_cndmask_b32_e32 v84, v234, v84, vcc
	v_cmp_le_i32_e32 vcc, v14, v237
	v_add_u32_e32 v14, 0xffffff4b, v0
	s_nop 0
	v_cndmask_b32_e32 v85, v234, v85, vcc
	v_cmp_le_i32_e32 vcc, v14, v237
	v_add_u32_e32 v14, 0xffffff4c, v0
	s_nop 0
	v_cndmask_b32_e32 v86, v234, v86, vcc
	v_cmp_le_i32_e32 vcc, v14, v237
	v_add_u32_e32 v14, 0xffffff51, v0
	s_nop 0
	v_cndmask_b32_e32 v87, v234, v87, vcc
	v_cmp_le_i32_e32 vcc, v14, v237
	v_add_u32_e32 v14, 0xffffff52, v0
	s_nop 0
	v_cndmask_b32_e32 v88, v234, v88, vcc
	v_cmp_le_i32_e32 vcc, v14, v237
	v_add_u32_e32 v14, 0xffffff53, v0
	s_nop 0
	v_cndmask_b32_e32 v89, v234, v89, vcc
	v_cmp_le_i32_e32 vcc, v14, v237
	v_add_u32_e32 v14, 0xffffff54, v0
	s_nop 0
	v_cndmask_b32_e32 v90, v234, v90, vcc
	v_cmp_le_i32_e32 vcc, v14, v237
	v_add_u32_e32 v14, 0xffffff59, v0
	s_nop 0
	v_cndmask_b32_e32 v91, v234, v91, vcc
	v_cmp_le_i32_e32 vcc, v14, v237
	v_add_u32_e32 v14, 0xffffff5a, v0
	s_nop 0
	v_cndmask_b32_e32 v92, v234, v92, vcc
	v_cmp_le_i32_e32 vcc, v14, v237
	v_add_u32_e32 v14, 0xffffff5b, v0
	s_nop 0
	v_cndmask_b32_e32 v93, v234, v93, vcc
	v_cmp_le_i32_e32 vcc, v14, v237
	v_add_u32_e32 v14, 0xffffff5c, v0
	s_nop 0
	v_cndmask_b32_e32 v94, v234, v94, vcc
	v_cmp_le_i32_e32 vcc, v14, v237
	v_add_u32_e32 v14, 0xffffff61, v0
	s_nop 0
	v_cndmask_b32_e32 v95, v234, v95, vcc
	v_cmp_le_i32_e32 vcc, v14, v237
	v_add_u32_e32 v14, 0xffffff62, v0
	s_nop 0
	v_cndmask_b32_e32 v64, v234, v64, vcc
	v_cmp_le_i32_e32 vcc, v14, v237
	v_add_u32_e32 v14, 0xffffff63, v0
	s_nop 0
	v_cndmask_b32_e32 v65, v234, v65, vcc
	v_cmp_le_i32_e32 vcc, v14, v237
	v_add_u32_e32 v14, 0xffffff64, v0
	s_nop 0
	v_cndmask_b32_e32 v66, v234, v66, vcc
	v_cmp_le_i32_e32 vcc, v14, v237
	v_add_u32_e32 v14, 0xffffff69, v0
	s_nop 0
	v_cndmask_b32_e32 v67, v234, v67, vcc
	v_cmp_le_i32_e32 vcc, v14, v237
	v_add_u32_e32 v14, 0xffffff6a, v0
	s_nop 0
	v_cndmask_b32_e32 v68, v234, v68, vcc
	v_cmp_le_i32_e32 vcc, v14, v237
	v_add_u32_e32 v14, 0xffffff6b, v0
	s_nop 0
	v_cndmask_b32_e32 v69, v234, v69, vcc
	v_cmp_le_i32_e32 vcc, v14, v237
	v_add_u32_e32 v14, 0xffffff6c, v0
	s_nop 0
	v_cndmask_b32_e32 v70, v234, v70, vcc
	v_cmp_le_i32_e32 vcc, v14, v237
	v_add_u32_e32 v14, 0xffffff71, v0
	s_nop 0
	v_cndmask_b32_e32 v71, v234, v71, vcc
	v_cmp_le_i32_e32 vcc, v14, v237
	v_add_u32_e32 v14, 0xffffff72, v0
	s_nop 0
	v_cndmask_b32_e32 v72, v234, v72, vcc
	v_cmp_le_i32_e32 vcc, v14, v237
	v_add_u32_e32 v14, 0xffffff73, v0
	s_nop 0
	v_cndmask_b32_e32 v73, v234, v73, vcc
	v_cmp_le_i32_e32 vcc, v14, v237
	v_add_u32_e32 v14, 0xffffff74, v0
	s_nop 0
	v_cndmask_b32_e32 v74, v234, v74, vcc
	v_cmp_le_i32_e32 vcc, v14, v237
	v_add_u32_e32 v14, 0xffffff79, v0
	s_nop 0
	v_cndmask_b32_e32 v75, v234, v75, vcc
	v_cmp_le_i32_e32 vcc, v14, v237
	v_add_u32_e32 v14, 0xffffff7a, v0
	s_nop 0
	v_cndmask_b32_e32 v76, v234, v76, vcc
	v_cmp_le_i32_e32 vcc, v14, v237
	v_add_u32_e32 v14, 0xffffff7b, v0
	v_add_u32_e32 v0, 0xffffff7c, v0
	v_cndmask_b32_e32 v77, v234, v77, vcc
	v_cmp_le_i32_e32 vcc, v14, v237
	s_nop 1
	v_cndmask_b32_e32 v78, v234, v78, vcc
	v_cmp_le_i32_e32 vcc, v0, v237
	s_nop 1
	v_cndmask_b32_e32 v79, v234, v79, vcc

; #define MFMA32(a, b, c) __builtin_amdgcn_mfma_f32_32x32x16_bf16((a), (b), (c), 0, 0, 0)
; #define AT_SB __builtin_amdgcn_sched_barrier(0);
; template <int DQK, int MODE, bool QN, bool KN> ...
;     ...
;     if (active) {
;       f32x16 sacc[2];
;       const float sinit = fixed_shift ? -sbound : 0.f;
; #pragma unroll
;       for (int kb = 0; kb < 2; ++kb) {
; #pragma unroll
;         for (int i = 0; i < 16; ++i) sacc[kb][i] = sinit;
; #pragma unroll
;         for (int s = 0; s < NS; ++s) {
;           const bf16x8 kf = *(const bf16x8*)(sK + (kb * 32 + r) * KROW + s * 32 + h * 16);
;           sacc[kb] = MFMA32(kf, qf[s], sacc[kb]);
;         }
;       }
;       const bool diag = (MODE != 0) && (kt * 64 + 63 >= q0 + wave * 32);
;       if (MODE != 0 && diag) {
; #pragma unroll
;         for (int kb = 0; kb < 2; ++kb)
; #pragma unroll
;           for (int i = 0; i < 16; ++i) {
;             const int key = kt * 64 + kb * 32 + (i & 3) + 8 * (i >> 2) + 4 * h;
;             if (MODE == 1 ? (key > qrow) : (key >= qrow)) sacc[kb][i] = -INFINITY;
;           }
;       }
;     ...
;     AT_SB AT_GLOAD(rk1, rv1, sg + 3)
;     AT_SB compute(2 * sg + 2, 1); compute(2 * sg + 3, 1); AT_SB
.Lstg_b:
	s_min_i32 s2, s45, s13
	s_lshl_b32 s4, s2, 7
	v_add_u32_e32 v0, s4, v238
	v_mad_i64_i32 v[14:15], s[2:3], v0, s36, v[220:221]
	v_add_u32_e32 v0, s4, v239
	v_mad_i64_i32 v[64:65], s[2:3], v0, s36, v[222:223]
	v_add_u32_e32 v0, s4, v240
	global_load_dwordx4 v[184:187], v[14:15], off
	global_load_dwordx4 v[188:191], v[64:65], off
	v_mad_i64_i32 v[14:15], s[2:3], v0, s36, v[224:225]
	v_add_u32_e32 v0, s4, v241
	v_mad_i64_i32 v[64:65], s[2:3], v0, s37, v[218:219]
	v_add_u32_e32 v0, s4, v242
	global_load_dwordx4 v[192:195], v[14:15], off
	global_load_dwordx4 v[196:199], v[64:65], off
	v_mad_i64_i32 v[14:15], s[2:3], v0, s37, v[218:219]
	global_load_dwordx4 v[200:203], v[14:15], off
	s_add_i32 s2, s53, 0xffffff81
	v_cmp_le_i32_e32 vcc, s2, v243
	s_and_saveexec_b64 s[2:3], vcc
	s_cbranch_execz .LBB0_1228
	ds_read_b128 v[32:35], v251 offset:43008
	ds_read_b128 v[36:39], v251 offset:43040
	ds_read_b128 v[40:43], v251 offset:43072
	ds_read_b128 v[44:47], v251 offset:43104
	ds_read_b128 v[48:51], v251 offset:43136
	ds_read_b128 v[52:55], v251 offset:43168
	ds_read_b128 v[112:115], v251 offset:49664
	ds_read_b128 v[116:119], v251 offset:49696
	ds_read_b128 v[120:123], v251 offset:49728
	ds_read_b128 v[124:127], v251 offset:49760
	ds_read_b128 v[144:147], v251 offset:49792
	ds_read_b128 v[148:151], v251 offset:49824
	s_sub_i32 s4, s53, 64
	v_cmp_ge_i32_e32 vcc, s4, v236
	s_waitcnt lgkmcnt(11)
	v_mfma_f32_32x32x16_bf16 v[80:95], v[32:35], v[160:163], v[16:31]
	s_waitcnt lgkmcnt(10)
	v_mfma_f32_32x32x16_bf16 v[80:95], v[36:39], v[164:167], v[80:95]
	s_waitcnt lgkmcnt(9)
	v_mfma_f32_32x32x16_bf16 v[80:95], v[40:43], v[168:171], v[80:95]
	s_waitcnt lgkmcnt(8)
	v_mfma_f32_32x32x16_bf16 v[80:95], v[44:47], v[172:175], v[80:95]
	s_waitcnt lgkmcnt(7)
	v_mfma_f32_32x32x16_bf16 v[80:95], v[48:51], v[176:179], v[80:95]
	s_waitcnt lgkmcnt(6)
	v_mfma_f32_32x32x16_bf16 v[80:95], v[52:55], v[180:183], v[80:95]
	s_or_b64 s[10:11], s[0:1], vcc
	s_cbranch_scc0 .Lmfp_2
	s_waitcnt lgkmcnt(5)
	v_mfma_f32_32x32x16_bf16 v[64:79], v[112:115], v[160:163], v[16:31]
	s_waitcnt lgkmcnt(4)
	v_mfma_f32_32x32x16_bf16 v[64:79], v[116:119], v[164:167], v[64:79]
	s_waitcnt lgkmcnt(3)
	v_mfma_f32_32x32x16_bf16 v[64:79], v[120:123], v[168:171], v[64:79]
	s_waitcnt lgkmcnt(2)
	v_mfma_f32_32x32x16_bf16 v[64:79], v[124:127], v[172:175], v[64:79]
	s_waitcnt lgkmcnt(1)
	v_mfma_f32_32x32x16_bf16 v[64:79], v[144:147], v[176:179], v[64:79]
	s_waitcnt lgkmcnt(0)
	v_mfma_f32_32x32x16_bf16 v[64:79], v[148:151], v[180:183], v[64:79]
	s_and_saveexec_b64 s[10:11], vcc
	s_cbranch_execz .LBB0_1221
	v_add_u32_e32 v0, s53, v247
	v_add_u32_e32 v14, 0xffffff81, v0
	v_cmp_le_i32_e32 vcc, v14, v237
	v_add_u32_e32 v14, 0xffffff82, v0
	s_nop 0
	v_cndmask_b32_e32 v80, v234, v80, vcc
	v_cmp_le_i32_e32 vcc, v14, v237
	v_add_u32_e32 v14, 0xffffff83, v0
	s_nop 0
	v_cndmask_b32_e32 v81, v234, v81, vcc
	v_cmp_le_i32_e32 vcc, v14, v237
	v_add_u32_e32 v14, 0xffffff84, v0
	s_nop 0
	v_cndmask_b32_e32 v82, v234, v82, vcc
	v_cmp_le_i32_e32 vcc, v14, v237
	v_add_u32_e32 v14, 0xffffff89, v0
	s_nop 0
	v_cndmask_b32_e32 v83, v234, v83, vcc
	v_cmp_le_i32_e32 vcc, v14, v237
	v_add_u32_e32 v14, 0xffffff8a, v0
	s_nop 0
	v_cndmask_b32_e32 v84, v234, v84, vcc
	v_cmp_le_i32_e32 vcc, v14, v237
	v_add_u32_e32 v14, 0xffffff8b, v0
	s_nop 0
	v_cndmask_b32_e32 v85, v234, v85, vcc
	v_cmp_le_i32_e32 vcc, v14, v237
	v_add_u32_e32 v14, 0xffffff8c, v0
	s_nop 0
	v_cndmask_b32_e32 v86, v234, v86, vcc
	v_cmp_le_i32_e32 vcc, v14, v237
	v_add_u32_e32 v14, 0xffffff91, v0
	s_nop 0
	v_cndmask_b32_e32 v87, v234, v87, vcc
	v_cmp_le_i32_e32 vcc, v14, v237
	v_add_u32_e32 v14, 0xffffff92, v0
	s_nop 0
	v_cndmask_b32_e32 v88, v234, v88, vcc
	v_cmp_le_i32_e32 vcc, v14, v237
	v_add_u32_e32 v14, 0xffffff93, v0
	s_nop 0
	v_cndmask_b32_e32 v89, v234, v89, vcc
	v_cmp_le_i32_e32 vcc, v14, v237
	v_add_u32_e32 v14, 0xffffff94, v0
	s_nop 0
	v_cndmask_b32_e32 v90, v234, v90, vcc
	v_cmp_le_i32_e32 vcc, v14, v237
	v_add_u32_e32 v14, 0xffffff99, v0
	s_nop 0
	v_cndmask_b32_e32 v91, v234, v91, vcc
	v_cmp_le_i32_e32 vcc, v14, v237
	v_add_u32_e32 v14, 0xffffff9a, v0
	s_nop 0
	v_cndmask_b32_e32 v92, v234, v92, vcc
	v_cmp_le_i32_e32 vcc, v14, v237
	v_add_u32_e32 v14, 0xffffff9b, v0
	s_nop 0
	v_cndmask_b32_e32 v93, v234, v93, vcc
	v_cmp_le_i32_e32 vcc, v14, v237
	v_add_u32_e32 v14, 0xffffff9c, v0
	s_nop 0
	v_cndmask_b32_e32 v94, v234, v94, vcc
	v_cmp_le_i32_e32 vcc, v14, v237
	v_add_u32_e32 v14, 0xffffffa1, v0
	s_nop 0
	v_cndmask_b32_e32 v95, v234, v95, vcc
	v_cmp_le_i32_e32 vcc, v14, v237
	v_add_u32_e32 v14, 0xffffffa2, v0
	s_nop 0
	v_cndmask_b32_e32 v64, v234, v64, vcc
	v_cmp_le_i32_e32 vcc, v14, v237
	v_add_u32_e32 v14, 0xffffffa3, v0
	s_nop 0
	v_cndmask_b32_e32 v65, v234, v65, vcc
	v_cmp_le_i32_e32 vcc, v14, v237
	v_add_u32_e32 v14, 0xffffffa4, v0
	s_nop 0
	v_cndmask_b32_e32 v66, v234, v66, vcc
	v_cmp_le_i32_e32 vcc, v14, v237
	v_add_u32_e32 v14, 0xffffffa9, v0
	s_nop 0
	v_cndmask_b32_e32 v67, v234, v67, vcc
	v_cmp_le_i32_e32 vcc, v14, v237
	v_add_u32_e32 v14, 0xffffffaa, v0
	s_nop 0
	v_cndmask_b32_e32 v68, v234, v68, vcc
	v_cmp_le_i32_e32 vcc, v14, v237
	v_add_u32_e32 v14, 0xffffffab, v0
	s_nop 0
	v_cndmask_b32_e32 v69, v234, v69, vcc
	v_cmp_le_i32_e32 vcc, v14, v237
	v_add_u32_e32 v14, 0xffffffac, v0
	s_nop 0
	v_cndmask_b32_e32 v70, v234, v70, vcc
	v_cmp_le_i32_e32 vcc, v14, v237
	v_add_u32_e32 v14, 0xffffffb1, v0
	s_nop 0
	v_cndmask_b32_e32 v71, v234, v71, vcc
	v_cmp_le_i32_e32 vcc, v14, v237
	v_add_u32_e32 v14, 0xffffffb2, v0
	s_nop 0
	v_cndmask_b32_e32 v72, v234, v72, vcc
	v_cmp_le_i32_e32 vcc, v14, v237
	v_add_u32_e32 v14, 0xffffffb3, v0
	s_nop 0
	v_cndmask_b32_e32 v73, v234, v73, vcc
	v_cmp_le_i32_e32 vcc, v14, v237
	v_add_u32_e32 v14, 0xffffffb4, v0
	s_nop 0
	v_cndmask_b32_e32 v74, v234, v74, vcc
	v_cmp_le_i32_e32 vcc, v14, v237
	v_add_u32_e32 v14, 0xffffffb9, v0
	s_nop 0
	v_cndmask_b32_e32 v75, v234, v75, vcc
	v_cmp_le_i32_e32 vcc, v14, v237
	v_add_u32_e32 v14, 0xffffffba, v0
	s_nop 0
	v_cndmask_b32_e32 v76, v234, v76, vcc
	v_cmp_le_i32_e32 vcc, v14, v237
	v_add_u32_e32 v14, 0xffffffbb, v0
	v_add_u32_e32 v0, 0xffffffbc, v0
	v_cndmask_b32_e32 v77, v234, v77, vcc
	v_cmp_le_i32_e32 vcc, v14, v237
	s_nop 1
	v_cndmask_b32_e32 v78, v234, v78, vcc
	v_cmp_le_i32_e32 vcc, v0, v237
	s_nop 1
	v_cndmask_b32_e32 v79, v234, v79, vcc

; #define MFMA32(a, b, c) __builtin_amdgcn_mfma_f32_32x32x16_bf16((a), (b), (c), 0, 0, 0)
; template <int DQK, int MODE, bool QN, bool KN> ...
;     ...
;     if (active) {
;       f32x16 sacc[2];
;       const float sinit = fixed_shift ? -sbound : 0.f;
; #pragma unroll
;       for (int kb = 0; kb < 2; ++kb) {
; #pragma unroll
;         for (int i = 0; i < 16; ++i) sacc[kb][i] = sinit;
; #pragma unroll
;         for (int s = 0; s < NS; ++s) {
;           const bf16x8 kf = *(const bf16x8*)(sK + (kb * 32 + r) * KROW + s * 32 + h * 16);
;           sacc[kb] = MFMA32(kf, qf[s], sacc[kb]);
;         }
;       }
;       const bool diag = (MODE != 0) && (kt * 64 + 63 >= q0 + wave * 32);
;       if (MODE != 0 && diag) {
; #pragma unroll
;         for (int kb = 0; kb < 2; ++kb)
; #pragma unroll
;           for (int i = 0; i < 16; ++i) {
;             const int key = kt * 64 + kb * 32 + (i & 3) + 8 * (i >> 2) + 4 * h;
;             if (MODE == 1 ? (key > qrow) : (key >= qrow)) sacc[kb][i] = -INFINITY;
;           }
;       }
.LBB0_1228:
	s_or_b64 exec, exec, s[2:3]
	s_sub_i32 s2, s53, 63
	v_cmp_le_i32_e32 vcc, s2, v243
	s_and_saveexec_b64 s[2:3], vcc
	s_cbranch_execz .LBB0_1197
	ds_read_b128 v[32:35], v251 offset:56320
	ds_read_b128 v[36:39], v251 offset:56352
	ds_read_b128 v[40:43], v251 offset:56384
	ds_read_b128 v[44:47], v251 offset:56416
	ds_read_b128 v[48:51], v251 offset:56448
	ds_read_b128 v[52:55], v251 offset:56480
	ds_read_b128 v[112:115], v251 offset:62976
	ds_read_b128 v[116:119], v251 offset:63008
	ds_read_b128 v[120:123], v251 offset:63040
	ds_read_b128 v[124:127], v251 offset:63072
	ds_read_b128 v[144:147], v251 offset:63104
	ds_read_b128 v[148:151], v251 offset:63136
	v_cmp_ge_i32_e32 vcc, s53, v236
	s_waitcnt lgkmcnt(11)
	v_mfma_f32_32x32x16_bf16 v[80:95], v[32:35], v[160:163], v[16:31]
	s_waitcnt lgkmcnt(10)
	v_mfma_f32_32x32x16_bf16 v[80:95], v[36:39], v[164:167], v[80:95]
	s_waitcnt lgkmcnt(9)
	v_mfma_f32_32x32x16_bf16 v[80:95], v[40:43], v[168:171], v[80:95]
	s_waitcnt lgkmcnt(8)
	v_mfma_f32_32x32x16_bf16 v[80:95], v[44:47], v[172:175], v[80:95]
	s_waitcnt lgkmcnt(7)
	v_mfma_f32_32x32x16_bf16 v[80:95], v[48:51], v[176:179], v[80:95]
	s_waitcnt lgkmcnt(6)
	v_mfma_f32_32x32x16_bf16 v[80:95], v[52:55], v[180:183], v[80:95]
	s_or_b64 s[10:11], s[0:1], vcc
	s_cbranch_scc0 .Lmfp_3
	s_waitcnt lgkmcnt(5)
	v_mfma_f32_32x32x16_bf16 v[64:79], v[112:115], v[160:163], v[16:31]
	s_waitcnt lgkmcnt(4)
	v_mfma_f32_32x32x16_bf16 v[64:79], v[116:119], v[164:167], v[64:79]
	s_waitcnt lgkmcnt(3)
	v_mfma_f32_32x32x16_bf16 v[64:79], v[120:123], v[168:171], v[64:79]
	s_waitcnt lgkmcnt(2)
	v_mfma_f32_32x32x16_bf16 v[64:79], v[124:127], v[172:175], v[64:79]
	s_waitcnt lgkmcnt(1)
	v_mfma_f32_32x32x16_bf16 v[64:79], v[144:147], v[176:179], v[64:79]
	s_waitcnt lgkmcnt(0)
	v_mfma_f32_32x32x16_bf16 v[64:79], v[148:151], v[180:183], v[64:79]
	s_and_saveexec_b64 s[10:11], vcc
	s_cbranch_execz .LBB0_1231
	v_add_u32_e32 v0, s53, v247
	v_subrev_u32_e32 v14, 63, v0
	v_cmp_le_i32_e32 vcc, v14, v237
	v_subrev_u32_e32 v14, 62, v0
	s_nop 0
	v_cndmask_b32_e32 v80, v234, v80, vcc
	v_cmp_le_i32_e32 vcc, v14, v237
	v_subrev_u32_e32 v14, 61, v0
	s_nop 0
	v_cndmask_b32_e32 v81, v234, v81, vcc
	v_cmp_le_i32_e32 vcc, v14, v237
	v_subrev_u32_e32 v14, 60, v0
	s_nop 0
	v_cndmask_b32_e32 v82, v234, v82, vcc
	v_cmp_le_i32_e32 vcc, v14, v237
	v_subrev_u32_e32 v14, 55, v0
	s_nop 0
	v_cndmask_b32_e32 v83, v234, v83, vcc
	v_cmp_le_i32_e32 vcc, v14, v237
	v_subrev_u32_e32 v14, 54, v0
	s_nop 0
	v_cndmask_b32_e32 v84, v234, v84, vcc
	v_cmp_le_i32_e32 vcc, v14, v237
	v_subrev_u32_e32 v14, 53, v0
	s_nop 0
	v_cndmask_b32_e32 v85, v234, v85, vcc
	v_cmp_le_i32_e32 vcc, v14, v237
	v_subrev_u32_e32 v14, 52, v0
	s_nop 0
	v_cndmask_b32_e32 v86, v234, v86, vcc
	v_cmp_le_i32_e32 vcc, v14, v237
	v_subrev_u32_e32 v14, 47, v0
	s_nop 0
	v_cndmask_b32_e32 v87, v234, v87, vcc
	v_cmp_le_i32_e32 vcc, v14, v237
	v_subrev_u32_e32 v14, 46, v0
	s_nop 0
	v_cndmask_b32_e32 v88, v234, v88, vcc
	v_cmp_le_i32_e32 vcc, v14, v237
	v_subrev_u32_e32 v14, 45, v0
	s_nop 0
	v_cndmask_b32_e32 v89, v234, v89, vcc
	v_cmp_le_i32_e32 vcc, v14, v237
	v_subrev_u32_e32 v14, 44, v0
	s_nop 0
	v_cndmask_b32_e32 v90, v234, v90, vcc
	v_cmp_le_i32_e32 vcc, v14, v237
	v_subrev_u32_e32 v14, 39, v0
	s_nop 0
	v_cndmask_b32_e32 v91, v234, v91, vcc
	v_cmp_le_i32_e32 vcc, v14, v237
	v_subrev_u32_e32 v14, 38, v0
	s_nop 0
	v_cndmask_b32_e32 v92, v234, v92, vcc
	v_cmp_le_i32_e32 vcc, v14, v237
	v_subrev_u32_e32 v14, 37, v0
	s_nop 0
	v_cndmask_b32_e32 v93, v234, v93, vcc
	v_cmp_le_i32_e32 vcc, v14, v237
	v_subrev_u32_e32 v14, 36, v0
	s_nop 0
	v_cndmask_b32_e32 v94, v234, v94, vcc
	v_cmp_le_i32_e32 vcc, v14, v237
	v_subrev_u32_e32 v14, 31, v0
	s_nop 0
	v_cndmask_b32_e32 v95, v234, v95, vcc
	v_cmp_le_i32_e32 vcc, v14, v237
	v_subrev_u32_e32 v14, 30, v0
	s_nop 0
	v_cndmask_b32_e32 v64, v234, v64, vcc
	v_cmp_le_i32_e32 vcc, v14, v237
	v_subrev_u32_e32 v14, 29, v0
	s_nop 0
	v_cndmask_b32_e32 v65, v234, v65, vcc
	v_cmp_le_i32_e32 vcc, v14, v237
	v_subrev_u32_e32 v14, 28, v0
	s_nop 0
	v_cndmask_b32_e32 v66, v234, v66, vcc
	v_cmp_le_i32_e32 vcc, v14, v237
	v_subrev_u32_e32 v14, 23, v0
	s_nop 0
	v_cndmask_b32_e32 v67, v234, v67, vcc
	v_cmp_le_i32_e32 vcc, v14, v237
	v_subrev_u32_e32 v14, 22, v0
	s_nop 0
	v_cndmask_b32_e32 v68, v234, v68, vcc
	v_cmp_le_i32_e32 vcc, v14, v237
	v_subrev_u32_e32 v14, 21, v0
	s_nop 0
	v_cndmask_b32_e32 v69, v234, v69, vcc
	v_cmp_le_i32_e32 vcc, v14, v237
	v_subrev_u32_e32 v14, 20, v0
	s_nop 0
	v_cndmask_b32_e32 v70, v234, v70, vcc
	v_cmp_le_i32_e32 vcc, v14, v237
	v_add_u32_e32 v14, -15, v0
	s_nop 0
	v_cndmask_b32_e32 v71, v234, v71, vcc
	v_cmp_le_i32_e32 vcc, v14, v237
	v_add_u32_e32 v14, -14, v0
	s_nop 0
	v_cndmask_b32_e32 v72, v234, v72, vcc
	v_cmp_le_i32_e32 vcc, v14, v237
	v_add_u32_e32 v14, -13, v0
	s_nop 0
	v_cndmask_b32_e32 v73, v234, v73, vcc
	v_cmp_le_i32_e32 vcc, v14, v237
	v_add_u32_e32 v14, -12, v0
	s_nop 0
	v_cndmask_b32_e32 v74, v234, v74, vcc
	v_cmp_le_i32_e32 vcc, v14, v237
	v_add_u32_e32 v14, -7, v0
	s_nop 0
	v_cndmask_b32_e32 v75, v234, v75, vcc
	v_cmp_le_i32_e32 vcc, v14, v237
	v_add_u32_e32 v14, -6, v0
	s_nop 0
	v_cndmask_b32_e32 v76, v234, v76, vcc
	v_cmp_le_i32_e32 vcc, v14, v237
	v_add_u32_e32 v14, -5, v0
	v_add_u32_e32 v0, -4, v0
	v_cndmask_b32_e32 v77, v234, v77, vcc
	v_cmp_le_i32_e32 vcc, v14, v237
	s_nop 1
	v_cndmask_b32_e32 v78, v234, v78, vcc
	v_cmp_le_i32_e32 vcc, v0, v237
	s_nop 1
	v_cndmask_b32_e32 v79, v234, v79, vcc

; #define MFMA32(a, b, c) __builtin_amdgcn_mfma_f32_32x32x16_bf16((a), (b), (c), 0, 0, 0)
; template <int DQK, int MODE, bool QN, bool KN> ...
;     ...
;         for (int s = 0; s < NS; ++s) {
;           const bf16x8 kf = *(const bf16x8*)(sK + (kb * 32 + r) * KROW + s * 32 + h * 16);
;           sacc[kb] = MFMA32(kf, qf[s], sacc[kb]);
;         }
;       }
;     ...
;       } else if (fixed_shift) {
;         float ps = 0.f;
; #pragma unroll
;         for (int kb = 0; kb < 2; ++kb)
; #pragma unroll
;           for (int i = 0; i < 16; ++i) { const float pv = __builtin_amdgcn_exp2f(sacc[kb][i]); sacc[kb][i] = pv; ps += pv; }
;         l_run += ps;
.Lmfp_0:
	s_waitcnt lgkmcnt(5)
	v_mfma_f32_32x32x16_bf16 v[64:79], v[112:115], v[160:163], v[16:31]
	s_waitcnt lgkmcnt(4)
	v_mfma_f32_32x32x16_bf16 v[64:79], v[116:119], v[164:167], v[64:79]
	s_nop 7
	v_exp_f32_e32 v112, v80
	v_exp_f32_e32 v113, v81
	v_exp_f32_e32 v114, v82
	v_exp_f32_e32 v115, v83
	s_waitcnt lgkmcnt(3)
	v_mfma_f32_32x32x16_bf16 v[64:79], v[120:123], v[168:171], v[64:79]
	v_exp_f32_e32 v116, v84
	v_exp_f32_e32 v117, v85
	v_exp_f32_e32 v118, v86
	v_exp_f32_e32 v119, v87
	s_waitcnt lgkmcnt(2)
	v_mfma_f32_32x32x16_bf16 v[64:79], v[124:127], v[172:175], v[64:79]
	v_exp_f32_e32 v120, v88
	v_exp_f32_e32 v121, v89
	v_exp_f32_e32 v122, v90
	v_exp_f32_e32 v123, v91
	s_waitcnt lgkmcnt(1)
	v_mfma_f32_32x32x16_bf16 v[64:79], v[144:147], v[176:179], v[64:79]
	v_exp_f32_e32 v124, v92
	v_exp_f32_e32 v125, v93
	v_exp_f32_e32 v126, v94
	v_exp_f32_e32 v127, v95
	s_waitcnt lgkmcnt(0)
	v_mfma_f32_32x32x16_bf16 v[64:79], v[148:151], v[180:183], v[64:79]
	v_add_f32_e32 v0, 0, v112
	v_add_f32_e32 v0, v113, v0
	v_add_f32_e32 v0, v114, v0
	v_add_f32_e32 v0, v115, v0
	v_add_f32_e32 v0, v116, v0
	v_add_f32_e32 v0, v117, v0
	v_add_f32_e32 v0, v118, v0
	v_add_f32_e32 v0, v119, v0
	v_add_f32_e32 v0, v120, v0
	v_add_f32_e32 v0, v121, v0
	v_add_f32_e32 v0, v122, v0
	v_add_f32_e32 v0, v123, v0
	v_add_f32_e32 v0, v124, v0
	v_add_f32_e32 v0, v125, v0
	v_add_f32_e32 v0, v126, v0
	v_add_f32_e32 v0, v127, v0
	v_exp_f32_e32 v144, v64
	v_exp_f32_e32 v145, v65
	v_add_f32_e32 v0, v144, v0
	v_exp_f32_e32 v146, v66
	v_add_f32_e32 v0, v145, v0
	v_exp_f32_e32 v147, v67
	v_add_f32_e32 v0, v146, v0
	v_exp_f32_e32 v148, v68
	v_add_f32_e32 v0, v147, v0
	v_exp_f32_e32 v149, v69
	v_add_f32_e32 v0, v148, v0
	v_exp_f32_e32 v150, v70
	v_add_f32_e32 v0, v149, v0
	v_exp_f32_e32 v151, v71
	v_add_f32_e32 v0, v150, v0
	v_exp_f32_e32 v152, v72
	v_add_f32_e32 v0, v151, v0
	v_exp_f32_e32 v153, v73
	v_add_f32_e32 v0, v152, v0
	v_exp_f32_e32 v154, v74
	v_add_f32_e32 v0, v153, v0
	v_exp_f32_e32 v155, v75
	v_add_f32_e32 v0, v154, v0
	v_exp_f32_e32 v156, v76
	v_add_f32_e32 v0, v155, v0
	v_exp_f32_e32 v157, v77
	v_add_f32_e32 v0, v156, v0
	v_exp_f32_e32 v158, v78
	v_add_f32_e32 v0, v157, v0
	v_exp_f32_e32 v159, v79
	v_add_f32_e32 v0, v158, v0
	v_mov_b32_e32 v14, v252
	v_add_f32_e32 v0, v159, v0
	v_add_f32_e32 v15, v253, v0
	s_branch .LBB0_1207
